# MLA: waves 0-3 issue the next tile's LDS transfers behind their first QK MFMA (shorter tile head between the barrier and the first MFMA)
# speedup vs baseline: 1.0071x; 1.0071x over previous
; __device__ __forceinline__ void finishSM9(f32x16& p0, f32x16& p1, float alpha, float& l_reg, v8i32& p8) {
; #pragma unroll
;   for (int r = 0; r < 16; ++r) { p0[r] = __builtin_amdgcn_exp2f(p0[r]); p1[r] = __builtin_amdgcn_exp2f(p1[r]); }
;   float ps = 0;
; #pragma unroll
;   for (int r = 0; r < 16; ++r) ps += p0[r];
; #pragma unroll
;   for (int r = 0; r < 16; ++r) ps += p1[r];
;   { auto rr = __builtin_amdgcn_permlane32_swap(__float_as_uint(ps), __float_as_uint(ps), false, false);
;     ps = __uint_as_float(rr[0]) + __uint_as_float(rr[1]); }
;   l_reg = l_reg * alpha + ps;
; #pragma unroll
;   for (int g = 0; g < 4; ++g) {
;     int w = __builtin_amdgcn_cvt_pk_fp8_f32(p0[4 * g], p0[4 * g + 1], 0, false); p8[g] = __builtin_amdgcn_cvt_pk_fp8_f32(p0[4 * g + 2], p0[4 * g + 3], w, true);
;     int u = __builtin_amdgcn_cvt_pk_fp8_f32(p1[4 * g], p1[4 * g + 1], 0, false); p8[4 + g] = __builtin_amdgcn_cvt_pk_fp8_f32(p1[4 * g + 2], p1[4 * g + 3], u, true); }
; }
; __device__ __forceinline__ void pv8(f32x16* o, const char* Vt, const v8i32 p8, int r32, int hi) {
;   const int sw = (r32 >> 2) & 3, a0 = r32 * 64 + (((hi * 2) ^ sw) << 4), a1 = r32 * 64 + (((hi * 2 + 1) ^ sw) << 4);
; #pragma unroll
;   for (int d0 = 0; d0 < 4; ++d0) {
;     const v8i32 vf = cat8(*reinterpret_cast<const v4i32*>(Vt + d0 * 2048 + a0), *reinterpret_cast<const v4i32*>(Vt + d0 * 2048 + a1));
;     o[d0] = __builtin_amdgcn_mfma_scale_f32_32x32x64_f8f6f4(p8, vf, o[d0], 0, 0, 0, 127, 0, 127); }
; }
; __device__ __forceinline__ void qkt9(f32x16& p0, f32x16& p1, const char* Kn, const char* Kr, const v8i32* qf, const float init, int r32, int hi) {
; #pragma unroll
;   for (int r = 0; r < 16; ++r) { p0[r] = init; p1[r] = init; }
; #pragma unroll
;   for (int s = 0; s < 2; ++s) { const int c0 = s * 4 + hi * 2;
;     const v8i32 a0 = cat8(*reinterpret_cast<const v4i32*>(Kn + KN8SW(r32, c0)), *reinterpret_cast<const v4i32*>(Kn + KN8SW(r32, c0 + 1)));
;     const v8i32 a1 = cat8(*reinterpret_cast<const v4i32*>(Kn + 4096 + KN8SW(r32, c0)), *reinterpret_cast<const v4i32*>(Kn + 4096 + KN8SW(r32, c0 + 1)));
;     p0 = __builtin_amdgcn_mfma_scale_f32_32x32x64_f8f6f4(a0, qf[s], p0, 0, 0, 0, 127, 0, 124);
;     p1 = __builtin_amdgcn_mfma_scale_f32_32x32x64_f8f6f4(a1, qf[s], p1, 0, 0, 0, 127, 0, 124); }
;   { const int c0 = hi * 2;
.LBB0_1321:
	ds_read_b128 v[114:117], v215 offset:24576
	ds_read_b128 v[118:121], v216 offset:24576
	ds_read_b128 v[222:225], v215 offset:28672
	ds_read_b128 v[226:229], v216 offset:28672
	v_exp_f32_e32 v0, v82
	v_exp_f32_e32 v177, v83
	v_exp_f32_e32 v179, v84
	v_exp_f32_e32 v254, v85
	v_add_f32_e32 v219, v0, v177
	v_cvt_pk_fp8_f32 v246, v0, v177
	v_add_f32_e32 v219, v179, v219
	v_add_f32_e32 v219, v254, v219
	v_cvt_pk_fp8_f32 v246, v179, v254 op_sel:[0,0,1]
	s_waitcnt lgkmcnt(2)
	v_mfma_scale_f32_32x32x64_f8f6f4 v[114:129], v[114:121], v[146:153], v[230:245], v194, v193 op_sel_hi:[0,0,0]
	s_add_i32 m0, s98, 0xa800
	s_nop 0
	global_load_lds_dwordx4 v176, s[18:19]
	s_add_i32 m0, s98, 0xc800
	s_nop 0
	global_load_lds_dwordx4 v178, s[16:17]
	s_add_i32 m0, s98, 0xe800
	s_nop 0
	global_load_lds_dwordx4 v[180:181], off
	v_exp_f32_e32 v0, v86
	v_exp_f32_e32 v177, v87
	v_exp_f32_e32 v179, v88
	v_exp_f32_e32 v254, v89
	v_add_f32_e32 v219, v0, v219
	v_add_f32_e32 v219, v177, v219
	v_cvt_pk_fp8_f32 v247, v0, v177
	v_add_f32_e32 v219, v179, v219
	v_add_f32_e32 v219, v254, v219
	v_cvt_pk_fp8_f32 v247, v179, v254 op_sel:[0,0,1]
	ds_read_b128 v[82:85], v213 offset:24576
	ds_read_b128 v[86:89], v214 offset:24576
	s_waitcnt lgkmcnt(2)
	v_mfma_scale_f32_32x32x64_f8f6f4 v[98:113], v[222:229], v[146:153], v[230:245], v194, v193 op_sel_hi:[0,0,0]
	ds_read_b128 v[222:225], v213 offset:28672
	ds_read_b128 v[226:229], v214 offset:28672
	v_exp_f32_e32 v0, v90
	v_exp_f32_e32 v177, v91
	v_exp_f32_e32 v179, v92
	v_exp_f32_e32 v254, v93
	v_add_f32_e32 v219, v0, v219
	v_add_f32_e32 v219, v177, v219
	v_cvt_pk_fp8_f32 v248, v0, v177
	v_add_f32_e32 v219, v179, v219
	v_add_f32_e32 v219, v254, v219
	v_cvt_pk_fp8_f32 v248, v179, v254 op_sel:[0,0,1]
	v_exp_f32_e32 v0, v94
	v_exp_f32_e32 v177, v95
	v_exp_f32_e32 v179, v96
	v_exp_f32_e32 v254, v97
	v_add_f32_e32 v219, v0, v219
	v_add_f32_e32 v219, v177, v219
	v_cvt_pk_fp8_f32 v249, v0, v177
	v_add_f32_e32 v219, v179, v219
	v_add_f32_e32 v219, v254, v219
	v_cvt_pk_fp8_f32 v249, v179, v254 op_sel:[0,0,1]
	ds_read_b128 v[90:93], v185 offset:36864
	ds_read_b128 v[94:97], v186 offset:36864
	s_waitcnt lgkmcnt(4)
	v_mfma_scale_f32_32x32x64_f8f6f4 v[114:129], v[82:89], v[138:145], v[114:129], v194, v193 op_sel_hi:[0,0,0]
	v_exp_f32_e32 v0, v66
	v_exp_f32_e32 v177, v67
	v_exp_f32_e32 v179, v68
	v_exp_f32_e32 v254, v69
	v_add_f32_e32 v219, v0, v219
	v_add_f32_e32 v219, v177, v219
	v_cvt_pk_fp8_f32 v250, v0, v177
	v_add_f32_e32 v219, v179, v219
	v_add_f32_e32 v219, v254, v219
	v_cvt_pk_fp8_f32 v250, v179, v254 op_sel:[0,0,1]
	s_waitcnt lgkmcnt(2)
	v_mfma_scale_f32_32x32x64_f8f6f4 v[98:113], v[222:229], v[138:145], v[98:113], v194, v193 op_sel_hi:[0,0,0]
	ds_read_b128 v[222:225], v185 offset:38912
	ds_read_b128 v[226:229], v186 offset:38912
	v_exp_f32_e32 v0, v70
	v_exp_f32_e32 v177, v71
	v_exp_f32_e32 v179, v72
	v_exp_f32_e32 v254, v73
	v_add_f32_e32 v219, v0, v219
	v_add_f32_e32 v219, v177, v219
	v_cvt_pk_fp8_f32 v251, v0, v177
	v_add_f32_e32 v219, v179, v219
	v_add_f32_e32 v219, v254, v219
	v_cvt_pk_fp8_f32 v251, v179, v254 op_sel:[0,0,1]
	v_exp_f32_e32 v0, v74
	v_exp_f32_e32 v177, v75
	v_exp_f32_e32 v179, v76
	v_exp_f32_e32 v254, v77
	v_add_f32_e32 v219, v0, v219
	v_add_f32_e32 v219, v177, v219
	v_cvt_pk_fp8_f32 v252, v0, v177
	v_add_f32_e32 v219, v179, v219
	v_add_f32_e32 v219, v254, v219
	v_cvt_pk_fp8_f32 v252, v179, v254 op_sel:[0,0,1]
	s_waitcnt lgkmcnt(2)
	v_mfma_scale_f32_32x32x64_f8f6f4 v[114:129], v[90:97], v[130:137], v[114:129], v194, v193 op_sel_hi:[0,0,0]
	v_exp_f32_e32 v0, v78
	v_exp_f32_e32 v177, v79
	v_exp_f32_e32 v179, v80
	v_exp_f32_e32 v254, v81
	v_add_f32_e32 v219, v0, v219
	v_add_f32_e32 v219, v177, v219
	v_cvt_pk_fp8_f32 v253, v0, v177
	v_add_f32_e32 v219, v179, v219
	v_add_f32_e32 v219, v254, v219
	v_cvt_pk_fp8_f32 v253, v179, v254 op_sel:[0,0,1]
	ds_read_b128 v[90:93], v185 offset:0
	ds_read_b128 v[94:97], v186 offset:0
	ds_read_b128 v[82:85], v185 offset:2048
	ds_read_b128 v[86:89], v186 offset:2048
	ds_read_b128 v[74:77], v185 offset:4096
	ds_read_b128 v[78:81], v186 offset:4096
	ds_read_b128 v[66:69], v185 offset:6144
	ds_read_b128 v[70:73], v186 offset:6144
	s_waitcnt lgkmcnt(8)
	v_mfma_scale_f32_32x32x64_f8f6f4 v[98:113], v[222:229], v[130:137], v[98:113], v194, v193 op_sel_hi:[0,0,0]
	v_mov_b32_e32 v0, v219
	s_nop 1
	v_permlane32_swap_b32_e32 v219, v0
	v_add_f32_e32 v219, v219, v0
	v_fma_f32 v209, v209, v218, v219
	v_add_u32_e32 v176, 0x2000, v176
	v_add_u32_e32 v178, 0x20000, v178
	s_mov_b64 s[20:21], 0x1000
	v_lshl_add_u64 v[180:181], v[180:181], 0, s[20:21]
	v_max_f32_e32 v177, v114, v115
	v_max3_f32 v177, v177, v116, v117
	v_max3_f32 v177, v177, v118, v119
	v_max3_f32 v177, v177, v120, v121
	v_max3_f32 v177, v177, v122, v123
	v_max3_f32 v177, v177, v124, v125
	v_max3_f32 v177, v177, v126, v127
	v_max3_f32 v177, v177, v128, v129
	s_waitcnt lgkmcnt(6)
	v_mfma_scale_f32_32x32x64_f8f6f4 v[50:65], v[246:253], v[90:97], v[50:65], v194, v194 op_sel_hi:[0,0,0]
	v_max_f32_e32 v0, v98, v99
	v_max3_f32 v0, v0, v100, v101
	v_max3_f32 v0, v0, v102, v103
	s_waitcnt lgkmcnt(4)
	v_mfma_scale_f32_32x32x64_f8f6f4 v[34:49], v[246:253], v[82:89], v[34:49], v194, v194 op_sel_hi:[0,0,0]
	v_max3_f32 v0, v0, v104, v105
	v_max3_f32 v0, v0, v106, v107
	v_max3_f32 v0, v0, v108, v109
	s_waitcnt lgkmcnt(2)
	v_mfma_scale_f32_32x32x64_f8f6f4 v[18:33], v[246:253], v[74:81], v[18:33], v194, v194 op_sel_hi:[0,0,0]
	v_max3_f32 v0, v0, v110, v111
	v_max3_f32 v0, v0, v112, v113
	v_max_f32_e32 v177, v177, v0
	v_mov_b32_e32 v0, v177
	v_mov_b32_e32 v221, 1.0
	s_waitcnt lgkmcnt(0)
	v_mfma_scale_f32_32x32x64_f8f6f4 v[2:17], v[246:253], v[66:73], v[2:17], v194, v194 op_sel_hi:[0,0,0]
	s_waitcnt vmcnt(0)
	s_waitcnt lgkmcnt(0)
	s_barrier
	v_permlane32_swap_b32_e32 v177, v0
	v_max_f32_e32 v177, v177, v0
	v_cmp_ge_f32_e32 vcc, s90, v177
	s_cmp_eq_u64 vcc, exec
	s_cbranch_scc0 .Lmla_h0_newmax
; __device__ __forceinline__ void finishSM9(f32x16& p0, f32x16& p1, float alpha, float& l_reg, v8i32& p8) {
; #pragma unroll
;   for (int r = 0; r < 16; ++r) { p0[r] = __builtin_amdgcn_exp2f(p0[r]); p1[r] = __builtin_amdgcn_exp2f(p1[r]); }
;   float ps = 0;
; #pragma unroll
;   for (int r = 0; r < 16; ++r) ps += p0[r];
; #pragma unroll
;   for (int r = 0; r < 16; ++r) ps += p1[r];
;   { auto rr = __builtin_amdgcn_permlane32_swap(__float_as_uint(ps), __float_as_uint(ps), false, false);
;     ps = __uint_as_float(rr[0]) + __uint_as_float(rr[1]); }
;   l_reg = l_reg * alpha + ps;
; #pragma unroll
;   for (int g = 0; g < 4; ++g) {
;     int w = __builtin_amdgcn_cvt_pk_fp8_f32(p0[4 * g], p0[4 * g + 1], 0, false); p8[g] = __builtin_amdgcn_cvt_pk_fp8_f32(p0[4 * g + 2], p0[4 * g + 3], w, true);
;     int u = __builtin_amdgcn_cvt_pk_fp8_f32(p1[4 * g], p1[4 * g + 1], 0, false); p8[4 + g] = __builtin_amdgcn_cvt_pk_fp8_f32(p1[4 * g + 2], p1[4 * g + 3], u, true); }
; }
; __device__ __forceinline__ void pv8(f32x16* o, const char* Vt, const v8i32 p8, int r32, int hi) {
;   const int sw = (r32 >> 2) & 3, a0 = r32 * 64 + (((hi * 2) ^ sw) << 4), a1 = r32 * 64 + (((hi * 2 + 1) ^ sw) << 4);
; #pragma unroll
;   for (int d0 = 0; d0 < 4; ++d0) {
;     const v8i32 vf = cat8(*reinterpret_cast<const v4i32*>(Vt + d0 * 2048 + a0), *reinterpret_cast<const v4i32*>(Vt + d0 * 2048 + a1));
;     o[d0] = __builtin_amdgcn_mfma_scale_f32_32x32x64_f8f6f4(p8, vf, o[d0], 0, 0, 0, 127, 0, 127); }
; }
; __device__ __forceinline__ void qkt9(f32x16& p0, f32x16& p1, const char* Kn, const char* Kr, const v8i32* qf, const float init, int r32, int hi) {
; #pragma unroll
;   for (int r = 0; r < 16; ++r) { p0[r] = init; p1[r] = init; }
; #pragma unroll
;   for (int s = 0; s < 2; ++s) { const int c0 = s * 4 + hi * 2;
;     const v8i32 a0 = cat8(*reinterpret_cast<const v4i32*>(Kn + KN8SW(r32, c0)), *reinterpret_cast<const v4i32*>(Kn + KN8SW(r32, c0 + 1)));
;     const v8i32 a1 = cat8(*reinterpret_cast<const v4i32*>(Kn + 4096 + KN8SW(r32, c0)), *reinterpret_cast<const v4i32*>(Kn + 4096 + KN8SW(r32, c0 + 1)));
;     p0 = __builtin_amdgcn_mfma_scale_f32_32x32x64_f8f6f4(a0, qf[s], p0, 0, 0, 0, 127, 0, 124);
;     p1 = __builtin_amdgcn_mfma_scale_f32_32x32x64_f8f6f4(a1, qf[s], p1, 0, 0, 0, 127, 0, 124); }
;   { const int c0 = hi * 2;
.Lmla_h0_cont:
	ds_read_b128 v[82:85], v215 offset:51200
	ds_read_b128 v[86:89], v216 offset:51200
	ds_read_b128 v[222:225], v215 offset:55296
	ds_read_b128 v[226:229], v216 offset:55296
	v_exp_f32_e32 v0, v114
	v_exp_f32_e32 v177, v115
	v_exp_f32_e32 v179, v116
	v_exp_f32_e32 v254, v117
	v_add_f32_e32 v219, v0, v177
	v_cvt_pk_fp8_f32 v246, v0, v177
	v_add_f32_e32 v219, v179, v219
	v_add_f32_e32 v219, v254, v219
	v_cvt_pk_fp8_f32 v246, v179, v254 op_sel:[0,0,1]
	s_waitcnt lgkmcnt(2)
	v_mfma_scale_f32_32x32x64_f8f6f4 v[82:97], v[82:89], v[146:153], v[230:245], v194, v193 op_sel_hi:[0,0,0]
	s_add_i32 m0, s98, 0x0
	s_nop 0
	global_load_lds_dwordx4 v176, s[18:19]
	s_add_i32 m0, s98, 0x4000
	s_nop 0
	global_load_lds_dwordx4 v178, s[16:17]
	s_add_i32 m0, s98, 0x8000
	s_nop 0
	global_load_lds_dwordx4 v[180:181], off
	v_exp_f32_e32 v0, v118
	v_exp_f32_e32 v177, v119
	v_exp_f32_e32 v179, v120
	v_exp_f32_e32 v254, v121
	v_add_f32_e32 v219, v0, v219
	v_add_f32_e32 v219, v177, v219
	v_cvt_pk_fp8_f32 v247, v0, v177
	v_add_f32_e32 v219, v179, v219
	v_add_f32_e32 v219, v254, v219
	v_cvt_pk_fp8_f32 v247, v179, v254 op_sel:[0,0,1]
	ds_read_b128 v[114:117], v213 offset:51200
	ds_read_b128 v[118:121], v214 offset:51200
	s_waitcnt lgkmcnt(2)
	v_mfma_scale_f32_32x32x64_f8f6f4 v[66:81], v[222:229], v[146:153], v[230:245], v194, v193 op_sel_hi:[0,0,0]
	ds_read_b128 v[222:225], v213 offset:55296
	ds_read_b128 v[226:229], v214 offset:55296
	v_exp_f32_e32 v0, v122
	v_exp_f32_e32 v177, v123
	v_exp_f32_e32 v179, v124
	v_exp_f32_e32 v254, v125
	v_add_f32_e32 v219, v0, v219
	v_add_f32_e32 v219, v177, v219
	v_cvt_pk_fp8_f32 v248, v0, v177
	v_add_f32_e32 v219, v179, v219
	v_add_f32_e32 v219, v254, v219
	v_cvt_pk_fp8_f32 v248, v179, v254 op_sel:[0,0,1]
	v_exp_f32_e32 v0, v126
	v_exp_f32_e32 v177, v127
	v_exp_f32_e32 v179, v128
	v_exp_f32_e32 v254, v129
	v_add_f32_e32 v219, v0, v219
	v_add_f32_e32 v219, v177, v219
	v_cvt_pk_fp8_f32 v249, v0, v177
	v_add_f32_e32 v219, v179, v219
	v_add_f32_e32 v219, v254, v219
	v_cvt_pk_fp8_f32 v249, v179, v254 op_sel:[0,0,1]
	ds_read_b128 v[122:125], v185 offset:59392
	ds_read_b128 v[126:129], v186 offset:59392
	s_waitcnt lgkmcnt(4)
	v_mfma_scale_f32_32x32x64_f8f6f4 v[82:97], v[114:121], v[138:145], v[82:97], v194, v193 op_sel_hi:[0,0,0]
	v_exp_f32_e32 v0, v98
	v_exp_f32_e32 v177, v99
	v_exp_f32_e32 v179, v100
	v_exp_f32_e32 v254, v101
	v_add_f32_e32 v219, v0, v219
	v_add_f32_e32 v219, v177, v219
	v_cvt_pk_fp8_f32 v250, v0, v177
	v_add_f32_e32 v219, v179, v219
	v_add_f32_e32 v219, v254, v219
	v_cvt_pk_fp8_f32 v250, v179, v254 op_sel:[0,0,1]
	s_waitcnt lgkmcnt(2)
	v_mfma_scale_f32_32x32x64_f8f6f4 v[66:81], v[222:229], v[138:145], v[66:81], v194, v193 op_sel_hi:[0,0,0]
	ds_read_b128 v[222:225], v185 offset:61440
	ds_read_b128 v[226:229], v186 offset:61440
	v_exp_f32_e32 v0, v102
	v_exp_f32_e32 v177, v103
	v_exp_f32_e32 v179, v104
	v_exp_f32_e32 v254, v105
	v_add_f32_e32 v219, v0, v219
	v_add_f32_e32 v219, v177, v219
	v_cvt_pk_fp8_f32 v251, v0, v177
	v_add_f32_e32 v219, v179, v219
	v_add_f32_e32 v219, v254, v219
	v_cvt_pk_fp8_f32 v251, v179, v254 op_sel:[0,0,1]
	v_exp_f32_e32 v0, v106
	v_exp_f32_e32 v177, v107
	v_exp_f32_e32 v179, v108
	v_exp_f32_e32 v254, v109
	v_add_f32_e32 v219, v0, v219
	v_add_f32_e32 v219, v177, v219
	v_cvt_pk_fp8_f32 v252, v0, v177
	v_add_f32_e32 v219, v179, v219
	v_add_f32_e32 v219, v254, v219
	v_cvt_pk_fp8_f32 v252, v179, v254 op_sel:[0,0,1]
	s_waitcnt lgkmcnt(2)
	v_mfma_scale_f32_32x32x64_f8f6f4 v[82:97], v[122:129], v[130:137], v[82:97], v194, v193 op_sel_hi:[0,0,0]
	v_exp_f32_e32 v0, v110
	v_exp_f32_e32 v177, v111
	v_exp_f32_e32 v179, v112
	v_exp_f32_e32 v254, v113
	v_add_f32_e32 v219, v0, v219
	v_add_f32_e32 v219, v177, v219
	v_cvt_pk_fp8_f32 v253, v0, v177
	v_add_f32_e32 v219, v179, v219
	v_add_f32_e32 v219, v254, v219
	v_cvt_pk_fp8_f32 v253, v179, v254 op_sel:[0,0,1]
	ds_read_b128 v[122:125], v185 offset:8192
	ds_read_b128 v[126:129], v186 offset:8192
	ds_read_b128 v[114:117], v185 offset:10240
	ds_read_b128 v[118:121], v186 offset:10240
	ds_read_b128 v[106:109], v185 offset:12288
	ds_read_b128 v[110:113], v186 offset:12288
	ds_read_b128 v[98:101], v185 offset:14336
	ds_read_b128 v[102:105], v186 offset:14336
	s_waitcnt lgkmcnt(8)
	v_mfma_scale_f32_32x32x64_f8f6f4 v[66:81], v[222:229], v[130:137], v[66:81], v194, v193 op_sel_hi:[0,0,0]
	v_mov_b32_e32 v0, v219
	s_nop 1
	v_permlane32_swap_b32_e32 v219, v0
	v_add_f32_e32 v219, v219, v0
	v_fma_f32 v209, v209, v221, v219
	v_add_u32_e32 v176, 0x2000, v176
	v_add_u32_e32 v178, 0x20000, v178
	s_mov_b64 s[20:21], 0x1000
	v_lshl_add_u64 v[180:181], v[180:181], 0, s[20:21]
	v_max_f32_e32 v177, v82, v83
	v_max3_f32 v177, v177, v84, v85
	v_max3_f32 v177, v177, v86, v87
	v_max3_f32 v177, v177, v88, v89
	v_max3_f32 v177, v177, v90, v91
	v_max3_f32 v177, v177, v92, v93
	v_max3_f32 v177, v177, v94, v95
	v_max3_f32 v177, v177, v96, v97
	s_waitcnt lgkmcnt(6)
	v_mfma_scale_f32_32x32x64_f8f6f4 v[50:65], v[246:253], v[122:129], v[50:65], v194, v194 op_sel_hi:[0,0,0]
	v_max_f32_e32 v0, v66, v67
	v_max3_f32 v0, v0, v68, v69
	v_max3_f32 v0, v0, v70, v71
	s_waitcnt lgkmcnt(4)
	v_mfma_scale_f32_32x32x64_f8f6f4 v[34:49], v[246:253], v[114:121], v[34:49], v194, v194 op_sel_hi:[0,0,0]
	v_max3_f32 v0, v0, v72, v73
	v_max3_f32 v0, v0, v74, v75
	v_max3_f32 v0, v0, v76, v77
	s_waitcnt lgkmcnt(2)
	v_mfma_scale_f32_32x32x64_f8f6f4 v[18:33], v[246:253], v[106:113], v[18:33], v194, v194 op_sel_hi:[0,0,0]
	v_max3_f32 v0, v0, v78, v79
	v_max3_f32 v0, v0, v80, v81
	v_max_f32_e32 v177, v177, v0
	v_mov_b32_e32 v0, v177
	v_mov_b32_e32 v218, 1.0
	s_waitcnt lgkmcnt(0)
	v_mfma_scale_f32_32x32x64_f8f6f4 v[2:17], v[246:253], v[98:105], v[2:17], v194, v194 op_sel_hi:[0,0,0]
	s_waitcnt vmcnt(0)
	s_waitcnt lgkmcnt(0)
	s_barrier
	v_permlane32_swap_b32_e32 v177, v0
	v_max_f32_e32 v177, v177, v0
	v_cmp_ge_f32_e32 vcc, s90, v177
	s_cmp_eq_u64 vcc, exec
	s_cbranch_scc0 .Lmla_h1_newmax
; __device__ __forceinline__ void finishSM9(f32x16& p0, f32x16& p1, float alpha, float& l_reg, v8i32& p8) {
; #pragma unroll
;   for (int r = 0; r < 16; ++r) { p0[r] = __builtin_amdgcn_exp2f(p0[r]); p1[r] = __builtin_amdgcn_exp2f(p1[r]); }
;   float ps = 0;
; #pragma unroll
;   for (int r = 0; r < 16; ++r) ps += p0[r];
; #pragma unroll
;   for (int r = 0; r < 16; ++r) ps += p1[r];
;   { auto rr = __builtin_amdgcn_permlane32_swap(__float_as_uint(ps), __float_as_uint(ps), false, false);
;     ps = __uint_as_float(rr[0]) + __uint_as_float(rr[1]); }
;   l_reg = l_reg * alpha + ps;
; #pragma unroll
;   for (int g = 0; g < 4; ++g) {
;     int w = __builtin_amdgcn_cvt_pk_fp8_f32(p0[4 * g], p0[4 * g + 1], 0, false); p8[g] = __builtin_amdgcn_cvt_pk_fp8_f32(p0[4 * g + 2], p0[4 * g + 3], w, true);
;     int u = __builtin_amdgcn_cvt_pk_fp8_f32(p1[4 * g], p1[4 * g + 1], 0, false); p8[4 + g] = __builtin_amdgcn_cvt_pk_fp8_f32(p1[4 * g + 2], p1[4 * g + 3], u, true); }
; }
; __device__ __forceinline__ void pv8(f32x16* o, const char* Vt, const v8i32 p8, int r32, int hi) {
;   const int sw = (r32 >> 2) & 3, a0 = r32 * 64 + (((hi * 2) ^ sw) << 4), a1 = r32 * 64 + (((hi * 2 + 1) ^ sw) << 4);
; #pragma unroll
;   for (int d0 = 0; d0 < 4; ++d0) {
;     const v8i32 vf = cat8(*reinterpret_cast<const v4i32*>(Vt + d0 * 2048 + a0), *reinterpret_cast<const v4i32*>(Vt + d0 * 2048 + a1));
;     o[d0] = __builtin_amdgcn_mfma_scale_f32_32x32x64_f8f6f4(p8, vf, o[d0], 0, 0, 0, 127, 0, 127); }
; }
; __device__ __forceinline__ void qkt9(f32x16& p0, f32x16& p1, const char* Kn, const char* Kr, const v8i32* qf, const float init, int r32, int hi) {
; #pragma unroll
;   for (int r = 0; r < 16; ++r) { p0[r] = init; p1[r] = init; }
; #pragma unroll
;   for (int s = 0; s < 2; ++s) { const int c0 = s * 4 + hi * 2;
;     const v8i32 a0 = cat8(*reinterpret_cast<const v4i32*>(Kn + KN8SW(r32, c0)), *reinterpret_cast<const v4i32*>(Kn + KN8SW(r32, c0 + 1)));
;     const v8i32 a1 = cat8(*reinterpret_cast<const v4i32*>(Kn + 4096 + KN8SW(r32, c0)), *reinterpret_cast<const v4i32*>(Kn + 4096 + KN8SW(r32, c0 + 1)));
;     p0 = __builtin_amdgcn_mfma_scale_f32_32x32x64_f8f6f4(a0, qf[s], p0, 0, 0, 0, 127, 0, 124);
;     p1 = __builtin_amdgcn_mfma_scale_f32_32x32x64_f8f6f4(a1, qf[s], p1, 0, 0, 0, 127, 0, 124); }
;   { const int c0 = hi * 2;
.Lmla_h1_cont:
	ds_read_b128 v[114:117], v215 offset:16384
	ds_read_b128 v[118:121], v216 offset:16384
	ds_read_b128 v[222:225], v215 offset:20480
	ds_read_b128 v[226:229], v216 offset:20480
	v_exp_f32_e32 v0, v82
	v_exp_f32_e32 v177, v83
	v_exp_f32_e32 v179, v84
	v_exp_f32_e32 v254, v85
	v_add_f32_e32 v219, v0, v177
	v_cvt_pk_fp8_f32 v246, v0, v177
	v_add_f32_e32 v219, v179, v219
	v_add_f32_e32 v219, v254, v219
	v_cvt_pk_fp8_f32 v246, v179, v254 op_sel:[0,0,1]
	s_waitcnt lgkmcnt(2)
	v_mfma_scale_f32_32x32x64_f8f6f4 v[114:129], v[114:121], v[146:153], v[230:245], v194, v193 op_sel_hi:[0,0,0]
	s_add_i32 m0, s98, 0x2000
	s_nop 0
	global_load_lds_dwordx4 v176, s[18:19]
	s_add_i32 m0, s98, 0x6000
	s_nop 0
	global_load_lds_dwordx4 v178, s[16:17]
	s_add_i32 m0, s98, 0x9000
	s_nop 0
	global_load_lds_dwordx4 v[180:181], off
	v_exp_f32_e32 v0, v86
	v_exp_f32_e32 v177, v87
	v_exp_f32_e32 v179, v88
	v_exp_f32_e32 v254, v89
	v_add_f32_e32 v219, v0, v219
	v_add_f32_e32 v219, v177, v219
	v_cvt_pk_fp8_f32 v247, v0, v177
	v_add_f32_e32 v219, v179, v219
	v_add_f32_e32 v219, v254, v219
	v_cvt_pk_fp8_f32 v247, v179, v254 op_sel:[0,0,1]
	ds_read_b128 v[82:85], v213 offset:16384
	ds_read_b128 v[86:89], v214 offset:16384
	s_waitcnt lgkmcnt(2)
	v_mfma_scale_f32_32x32x64_f8f6f4 v[98:113], v[222:229], v[146:153], v[230:245], v194, v193 op_sel_hi:[0,0,0]
	ds_read_b128 v[222:225], v213 offset:20480
	ds_read_b128 v[226:229], v214 offset:20480
	v_exp_f32_e32 v0, v90
	v_exp_f32_e32 v177, v91
	v_exp_f32_e32 v179, v92
	v_exp_f32_e32 v254, v93
	v_add_f32_e32 v219, v0, v219
	v_add_f32_e32 v219, v177, v219
	v_cvt_pk_fp8_f32 v248, v0, v177
	v_add_f32_e32 v219, v179, v219
	v_add_f32_e32 v219, v254, v219
	v_cvt_pk_fp8_f32 v248, v179, v254 op_sel:[0,0,1]
	v_exp_f32_e32 v0, v94
	v_exp_f32_e32 v177, v95
	v_exp_f32_e32 v179, v96
	v_exp_f32_e32 v254, v97
	v_add_f32_e32 v219, v0, v219
	v_add_f32_e32 v219, v177, v219
	v_cvt_pk_fp8_f32 v249, v0, v177
	v_add_f32_e32 v219, v179, v219
	v_add_f32_e32 v219, v254, v219
	v_cvt_pk_fp8_f32 v249, v179, v254 op_sel:[0,0,1]
	ds_read_b128 v[90:93], v185 offset:32768
	ds_read_b128 v[94:97], v186 offset:32768
	s_waitcnt lgkmcnt(4)
	v_mfma_scale_f32_32x32x64_f8f6f4 v[114:129], v[82:89], v[138:145], v[114:129], v194, v193 op_sel_hi:[0,0,0]
	v_exp_f32_e32 v0, v66
	v_exp_f32_e32 v177, v67
	v_exp_f32_e32 v179, v68
	v_exp_f32_e32 v254, v69
	v_add_f32_e32 v219, v0, v219
	v_add_f32_e32 v219, v177, v219
	v_cvt_pk_fp8_f32 v250, v0, v177
	v_add_f32_e32 v219, v179, v219
	v_add_f32_e32 v219, v254, v219
	v_cvt_pk_fp8_f32 v250, v179, v254 op_sel:[0,0,1]
	s_waitcnt lgkmcnt(2)
	v_mfma_scale_f32_32x32x64_f8f6f4 v[98:113], v[222:229], v[138:145], v[98:113], v194, v193 op_sel_hi:[0,0,0]
	ds_read_b128 v[222:225], v185 offset:34816
	ds_read_b128 v[226:229], v186 offset:34816
	v_exp_f32_e32 v0, v70
	v_exp_f32_e32 v177, v71
	v_exp_f32_e32 v179, v72
	v_exp_f32_e32 v254, v73
	v_add_f32_e32 v219, v0, v219
	v_add_f32_e32 v219, v177, v219
	v_cvt_pk_fp8_f32 v251, v0, v177
	v_add_f32_e32 v219, v179, v219
	v_add_f32_e32 v219, v254, v219
	v_cvt_pk_fp8_f32 v251, v179, v254 op_sel:[0,0,1]
	v_exp_f32_e32 v0, v74
	v_exp_f32_e32 v177, v75
	v_exp_f32_e32 v179, v76
	v_exp_f32_e32 v254, v77
	v_add_f32_e32 v219, v0, v219
	v_add_f32_e32 v219, v177, v219
	v_cvt_pk_fp8_f32 v252, v0, v177
	v_add_f32_e32 v219, v179, v219
	v_add_f32_e32 v219, v254, v219
	v_cvt_pk_fp8_f32 v252, v179, v254 op_sel:[0,0,1]
	s_waitcnt lgkmcnt(2)
	v_mfma_scale_f32_32x32x64_f8f6f4 v[114:129], v[90:97], v[130:137], v[114:129], v194, v193 op_sel_hi:[0,0,0]
	v_exp_f32_e32 v0, v78
	v_exp_f32_e32 v177, v79
	v_exp_f32_e32 v179, v80
	v_exp_f32_e32 v254, v81
	v_add_f32_e32 v219, v0, v219
	v_add_f32_e32 v219, v177, v219
	v_cvt_pk_fp8_f32 v253, v0, v177
	v_add_f32_e32 v219, v179, v219
	v_add_f32_e32 v219, v254, v219
	v_cvt_pk_fp8_f32 v253, v179, v254 op_sel:[0,0,1]
	ds_read_b128 v[90:93], v185 offset:43008
	ds_read_b128 v[94:97], v186 offset:43008
	ds_read_b128 v[82:85], v185 offset:45056
	ds_read_b128 v[86:89], v186 offset:45056
	ds_read_b128 v[74:77], v185 offset:47104
	ds_read_b128 v[78:81], v186 offset:47104
	ds_read_b128 v[66:69], v185 offset:49152
	ds_read_b128 v[70:73], v186 offset:49152
	s_waitcnt lgkmcnt(8)
	v_mfma_scale_f32_32x32x64_f8f6f4 v[98:113], v[222:229], v[130:137], v[98:113], v194, v193 op_sel_hi:[0,0,0]
	v_mov_b32_e32 v0, v219
	s_nop 1
	v_permlane32_swap_b32_e32 v219, v0
	v_add_f32_e32 v219, v219, v0
	v_fma_f32 v209, v209, v218, v219
	v_add_u32_e32 v176, 0x2000, v176
	v_add_u32_e32 v178, 0x20000, v178
	s_mov_b64 s[20:21], 0x1000
	v_lshl_add_u64 v[180:181], v[180:181], 0, s[20:21]
	v_max_f32_e32 v177, v114, v115
	v_max3_f32 v177, v177, v116, v117
	v_max3_f32 v177, v177, v118, v119
	v_max3_f32 v177, v177, v120, v121
	v_max3_f32 v177, v177, v122, v123
	v_max3_f32 v177, v177, v124, v125
	v_max3_f32 v177, v177, v126, v127
	v_max3_f32 v177, v177, v128, v129
	s_waitcnt lgkmcnt(6)
	v_mfma_scale_f32_32x32x64_f8f6f4 v[50:65], v[246:253], v[90:97], v[50:65], v194, v194 op_sel_hi:[0,0,0]
	v_max_f32_e32 v0, v98, v99
	v_max3_f32 v0, v0, v100, v101
	v_max3_f32 v0, v0, v102, v103
	s_waitcnt lgkmcnt(4)
	v_mfma_scale_f32_32x32x64_f8f6f4 v[34:49], v[246:253], v[82:89], v[34:49], v194, v194 op_sel_hi:[0,0,0]
	v_max3_f32 v0, v0, v104, v105
	v_max3_f32 v0, v0, v106, v107
	v_max3_f32 v0, v0, v108, v109
	s_waitcnt lgkmcnt(2)
	v_mfma_scale_f32_32x32x64_f8f6f4 v[18:33], v[246:253], v[74:81], v[18:33], v194, v194 op_sel_hi:[0,0,0]
	v_max3_f32 v0, v0, v110, v111
	v_max3_f32 v0, v0, v112, v113
	v_max_f32_e32 v177, v177, v0
	v_mov_b32_e32 v0, v177
	v_mov_b32_e32 v221, 1.0
	s_waitcnt lgkmcnt(0)
	v_mfma_scale_f32_32x32x64_f8f6f4 v[2:17], v[246:253], v[66:73], v[2:17], v194, v194 op_sel_hi:[0,0,0]
	s_waitcnt vmcnt(0)
	s_waitcnt lgkmcnt(0)
	s_barrier
	v_permlane32_swap_b32_e32 v177, v0
	v_max_f32_e32 v177, v177, v0
	v_cmp_ge_f32_e32 vcc, s90, v177
	s_cmp_eq_u64 vcc, exec
	s_cbranch_scc0 .Lmla_h2_newmax
; __device__ __forceinline__ void finishSM9(f32x16& p0, f32x16& p1, float alpha, float& l_reg, v8i32& p8) {
; #pragma unroll
;   for (int r = 0; r < 16; ++r) { p0[r] = __builtin_amdgcn_exp2f(p0[r]); p1[r] = __builtin_amdgcn_exp2f(p1[r]); }
;   float ps = 0;
; #pragma unroll
;   for (int r = 0; r < 16; ++r) ps += p0[r];
; #pragma unroll
;   for (int r = 0; r < 16; ++r) ps += p1[r];
;   { auto rr = __builtin_amdgcn_permlane32_swap(__float_as_uint(ps), __float_as_uint(ps), false, false);
;     ps = __uint_as_float(rr[0]) + __uint_as_float(rr[1]); }
;   l_reg = l_reg * alpha + ps;
; #pragma unroll
;   for (int g = 0; g < 4; ++g) {
;     int w = __builtin_amdgcn_cvt_pk_fp8_f32(p0[4 * g], p0[4 * g + 1], 0, false); p8[g] = __builtin_amdgcn_cvt_pk_fp8_f32(p0[4 * g + 2], p0[4 * g + 3], w, true);
;     int u = __builtin_amdgcn_cvt_pk_fp8_f32(p1[4 * g], p1[4 * g + 1], 0, false); p8[4 + g] = __builtin_amdgcn_cvt_pk_fp8_f32(p1[4 * g + 2], p1[4 * g + 3], u, true); }
; }
; __device__ __forceinline__ void pv8(f32x16* o, const char* Vt, const v8i32 p8, int r32, int hi) {
;   const int sw = (r32 >> 2) & 3, a0 = r32 * 64 + (((hi * 2) ^ sw) << 4), a1 = r32 * 64 + (((hi * 2 + 1) ^ sw) << 4);
; #pragma unroll
;   for (int d0 = 0; d0 < 4; ++d0) {
;     const v8i32 vf = cat8(*reinterpret_cast<const v4i32*>(Vt + d0 * 2048 + a0), *reinterpret_cast<const v4i32*>(Vt + d0 * 2048 + a1));
;     o[d0] = __builtin_amdgcn_mfma_scale_f32_32x32x64_f8f6f4(p8, vf, o[d0], 0, 0, 0, 127, 0, 127); }
; }
; __device__ __forceinline__ void qkt9(f32x16& p0, f32x16& p1, const char* Kn, const char* Kr, const v8i32* qf, const float init, int r32, int hi) {
; #pragma unroll
;   for (int r = 0; r < 16; ++r) { p0[r] = init; p1[r] = init; }
; #pragma unroll
;   for (int s = 0; s < 2; ++s) { const int c0 = s * 4 + hi * 2;
;     const v8i32 a0 = cat8(*reinterpret_cast<const v4i32*>(Kn + KN8SW(r32, c0)), *reinterpret_cast<const v4i32*>(Kn + KN8SW(r32, c0 + 1)));
;     const v8i32 a1 = cat8(*reinterpret_cast<const v4i32*>(Kn + 4096 + KN8SW(r32, c0)), *reinterpret_cast<const v4i32*>(Kn + 4096 + KN8SW(r32, c0 + 1)));
;     p0 = __builtin_amdgcn_mfma_scale_f32_32x32x64_f8f6f4(a0, qf[s], p0, 0, 0, 0, 127, 0, 124);
;     p1 = __builtin_amdgcn_mfma_scale_f32_32x32x64_f8f6f4(a1, qf[s], p1, 0, 0, 0, 127, 0, 124); }
;   { const int c0 = hi * 2;
.Lmla_h2_cont:
	ds_read_b128 v[82:85], v215 offset:24576
	ds_read_b128 v[86:89], v216 offset:24576
	ds_read_b128 v[222:225], v215 offset:28672
	ds_read_b128 v[226:229], v216 offset:28672
	v_exp_f32_e32 v0, v114
	v_exp_f32_e32 v177, v115
	v_exp_f32_e32 v179, v116
	v_exp_f32_e32 v254, v117
	v_add_f32_e32 v219, v0, v177
	v_cvt_pk_fp8_f32 v246, v0, v177
	v_add_f32_e32 v219, v179, v219
	v_add_f32_e32 v219, v254, v219
	v_cvt_pk_fp8_f32 v246, v179, v254 op_sel:[0,0,1]
	s_waitcnt lgkmcnt(2)
	v_mfma_scale_f32_32x32x64_f8f6f4 v[82:97], v[82:89], v[146:153], v[230:245], v194, v193 op_sel_hi:[0,0,0]
	s_add_i32 m0, s98, 0xa800
	s_nop 0
	global_load_lds_dwordx4 v176, s[18:19]
	s_add_i32 m0, s98, 0xc800
	s_nop 0
	global_load_lds_dwordx4 v178, s[16:17]
	s_add_i32 m0, s98, 0xe800
	s_nop 0
	global_load_lds_dwordx4 v[180:181], off
	v_exp_f32_e32 v0, v118
	v_exp_f32_e32 v177, v119
	v_exp_f32_e32 v179, v120
	v_exp_f32_e32 v254, v121
	v_add_f32_e32 v219, v0, v219
	v_add_f32_e32 v219, v177, v219
	v_cvt_pk_fp8_f32 v247, v0, v177
	v_add_f32_e32 v219, v179, v219
	v_add_f32_e32 v219, v254, v219
	v_cvt_pk_fp8_f32 v247, v179, v254 op_sel:[0,0,1]
	ds_read_b128 v[114:117], v213 offset:24576
	ds_read_b128 v[118:121], v214 offset:24576
	s_waitcnt lgkmcnt(2)
	v_mfma_scale_f32_32x32x64_f8f6f4 v[66:81], v[222:229], v[146:153], v[230:245], v194, v193 op_sel_hi:[0,0,0]
	ds_read_b128 v[222:225], v213 offset:28672
	ds_read_b128 v[226:229], v214 offset:28672
	v_exp_f32_e32 v0, v122
	v_exp_f32_e32 v177, v123
	v_exp_f32_e32 v179, v124
	v_exp_f32_e32 v254, v125
	v_add_f32_e32 v219, v0, v219
	v_add_f32_e32 v219, v177, v219
	v_cvt_pk_fp8_f32 v248, v0, v177
	v_add_f32_e32 v219, v179, v219
	v_add_f32_e32 v219, v254, v219
	v_cvt_pk_fp8_f32 v248, v179, v254 op_sel:[0,0,1]
	v_exp_f32_e32 v0, v126
	v_exp_f32_e32 v177, v127
	v_exp_f32_e32 v179, v128
	v_exp_f32_e32 v254, v129
	v_add_f32_e32 v219, v0, v219
	v_add_f32_e32 v219, v177, v219
	v_cvt_pk_fp8_f32 v249, v0, v177
	v_add_f32_e32 v219, v179, v219
	v_add_f32_e32 v219, v254, v219
	v_cvt_pk_fp8_f32 v249, v179, v254 op_sel:[0,0,1]
	ds_read_b128 v[122:125], v185 offset:36864
	ds_read_b128 v[126:129], v186 offset:36864
	s_waitcnt lgkmcnt(4)
	v_mfma_scale_f32_32x32x64_f8f6f4 v[82:97], v[114:121], v[138:145], v[82:97], v194, v193 op_sel_hi:[0,0,0]
	v_exp_f32_e32 v0, v98
	v_exp_f32_e32 v177, v99
	v_exp_f32_e32 v179, v100
	v_exp_f32_e32 v254, v101
	v_add_f32_e32 v219, v0, v219
	v_add_f32_e32 v219, v177, v219
	v_cvt_pk_fp8_f32 v250, v0, v177
	v_add_f32_e32 v219, v179, v219
	v_add_f32_e32 v219, v254, v219
	v_cvt_pk_fp8_f32 v250, v179, v254 op_sel:[0,0,1]
	s_waitcnt lgkmcnt(2)
	v_mfma_scale_f32_32x32x64_f8f6f4 v[66:81], v[222:229], v[138:145], v[66:81], v194, v193 op_sel_hi:[0,0,0]
	ds_read_b128 v[222:225], v185 offset:38912
	ds_read_b128 v[226:229], v186 offset:38912
	v_exp_f32_e32 v0, v102
	v_exp_f32_e32 v177, v103
	v_exp_f32_e32 v179, v104
	v_exp_f32_e32 v254, v105
	v_add_f32_e32 v219, v0, v219
	v_add_f32_e32 v219, v177, v219
	v_cvt_pk_fp8_f32 v251, v0, v177
	v_add_f32_e32 v219, v179, v219
	v_add_f32_e32 v219, v254, v219
	v_cvt_pk_fp8_f32 v251, v179, v254 op_sel:[0,0,1]
	v_exp_f32_e32 v0, v106
	v_exp_f32_e32 v177, v107
	v_exp_f32_e32 v179, v108
	v_exp_f32_e32 v254, v109
	v_add_f32_e32 v219, v0, v219
	v_add_f32_e32 v219, v177, v219
	v_cvt_pk_fp8_f32 v252, v0, v177
	v_add_f32_e32 v219, v179, v219
	v_add_f32_e32 v219, v254, v219
	v_cvt_pk_fp8_f32 v252, v179, v254 op_sel:[0,0,1]
	s_waitcnt lgkmcnt(2)
	v_mfma_scale_f32_32x32x64_f8f6f4 v[82:97], v[122:129], v[130:137], v[82:97], v194, v193 op_sel_hi:[0,0,0]
	v_exp_f32_e32 v0, v110
	v_exp_f32_e32 v177, v111
	v_exp_f32_e32 v179, v112
	v_exp_f32_e32 v254, v113
	v_add_f32_e32 v219, v0, v219
	v_add_f32_e32 v219, v177, v219
	v_cvt_pk_fp8_f32 v253, v0, v177
	v_add_f32_e32 v219, v179, v219
	v_add_f32_e32 v219, v254, v219
	v_cvt_pk_fp8_f32 v253, v179, v254 op_sel:[0,0,1]
	ds_read_b128 v[122:125], v185 offset:0
	ds_read_b128 v[126:129], v186 offset:0
	ds_read_b128 v[114:117], v185 offset:2048
	ds_read_b128 v[118:121], v186 offset:2048
	ds_read_b128 v[106:109], v185 offset:4096
	ds_read_b128 v[110:113], v186 offset:4096
	ds_read_b128 v[98:101], v185 offset:6144
	ds_read_b128 v[102:105], v186 offset:6144
	s_waitcnt lgkmcnt(8)
	v_mfma_scale_f32_32x32x64_f8f6f4 v[66:81], v[222:229], v[130:137], v[66:81], v194, v193 op_sel_hi:[0,0,0]
	v_mov_b32_e32 v0, v219
	s_nop 1
	v_permlane32_swap_b32_e32 v219, v0
	v_add_f32_e32 v219, v219, v0
	v_fma_f32 v209, v209, v221, v219
	v_add_u32_e32 v176, 0x2000, v176
	v_add_u32_e32 v178, 0x20000, v178
	s_mov_b64 s[20:21], 0x1000
	v_lshl_add_u64 v[180:181], v[180:181], 0, s[20:21]
	v_max_f32_e32 v177, v82, v83
	v_max3_f32 v177, v177, v84, v85
	v_max3_f32 v177, v177, v86, v87
	v_max3_f32 v177, v177, v88, v89
	v_max3_f32 v177, v177, v90, v91
	v_max3_f32 v177, v177, v92, v93
	v_max3_f32 v177, v177, v94, v95
	v_max3_f32 v177, v177, v96, v97
	s_waitcnt lgkmcnt(6)
	v_mfma_scale_f32_32x32x64_f8f6f4 v[50:65], v[246:253], v[122:129], v[50:65], v194, v194 op_sel_hi:[0,0,0]
	v_max_f32_e32 v0, v66, v67
	v_max3_f32 v0, v0, v68, v69
	v_max3_f32 v0, v0, v70, v71
	s_waitcnt lgkmcnt(4)
	v_mfma_scale_f32_32x32x64_f8f6f4 v[34:49], v[246:253], v[114:121], v[34:49], v194, v194 op_sel_hi:[0,0,0]
	v_max3_f32 v0, v0, v72, v73
	v_max3_f32 v0, v0, v74, v75
	v_max3_f32 v0, v0, v76, v77
	s_waitcnt lgkmcnt(2)
	v_mfma_scale_f32_32x32x64_f8f6f4 v[18:33], v[246:253], v[106:113], v[18:33], v194, v194 op_sel_hi:[0,0,0]
	v_max3_f32 v0, v0, v78, v79
	v_max3_f32 v0, v0, v80, v81
	v_max_f32_e32 v177, v177, v0
	v_mov_b32_e32 v0, v177
	v_mov_b32_e32 v218, 1.0
	s_waitcnt lgkmcnt(0)
	v_mfma_scale_f32_32x32x64_f8f6f4 v[2:17], v[246:253], v[98:105], v[2:17], v194, v194 op_sel_hi:[0,0,0]
	s_waitcnt vmcnt(0)
	s_waitcnt lgkmcnt(0)
	s_barrier
	v_permlane32_swap_b32_e32 v177, v0
	v_max_f32_e32 v177, v177, v0
	v_cmp_ge_f32_e32 vcc, s90, v177
	s_cmp_eq_u64 vcc, exec
	s_cbranch_scc0 .Lmla_h3_newmax
; __device__ __forceinline__ void finishSM9(f32x16& p0, f32x16& p1, float alpha, float& l_reg, v8i32& p8) {
; #pragma unroll
;   for (int r = 0; r < 16; ++r) { p0[r] = __builtin_amdgcn_exp2f(p0[r]); p1[r] = __builtin_amdgcn_exp2f(p1[r]); }
;   float ps = 0;
; #pragma unroll
;   for (int r = 0; r < 16; ++r) ps += p0[r];
; #pragma unroll
;   for (int r = 0; r < 16; ++r) ps += p1[r];
;   { auto rr = __builtin_amdgcn_permlane32_swap(__float_as_uint(ps), __float_as_uint(ps), false, false);
;     ps = __uint_as_float(rr[0]) + __uint_as_float(rr[1]); }
;   l_reg = l_reg * alpha + ps;
; #pragma unroll
;   for (int g = 0; g < 4; ++g) {
;     int w = __builtin_amdgcn_cvt_pk_fp8_f32(p0[4 * g], p0[4 * g + 1], 0, false); p8[g] = __builtin_amdgcn_cvt_pk_fp8_f32(p0[4 * g + 2], p0[4 * g + 3], w, true);
;     int u = __builtin_amdgcn_cvt_pk_fp8_f32(p1[4 * g], p1[4 * g + 1], 0, false); p8[4 + g] = __builtin_amdgcn_cvt_pk_fp8_f32(p1[4 * g + 2], p1[4 * g + 3], u, true); }
; }
; __device__ __forceinline__ void pv8(f32x16* o, const char* Vt, const v8i32 p8, int r32, int hi) {
;   const int sw = (r32 >> 2) & 3, a0 = r32 * 64 + (((hi * 2) ^ sw) << 4), a1 = r32 * 64 + (((hi * 2 + 1) ^ sw) << 4);
; #pragma unroll
;   for (int d0 = 0; d0 < 4; ++d0) {
;     const v8i32 vf = cat8(*reinterpret_cast<const v4i32*>(Vt + d0 * 2048 + a0), *reinterpret_cast<const v4i32*>(Vt + d0 * 2048 + a1));
;     o[d0] = __builtin_amdgcn_mfma_scale_f32_32x32x64_f8f6f4(p8, vf, o[d0], 0, 0, 0, 127, 0, 127); }
; }
; __device__ __forceinline__ void qkt9(f32x16& p0, f32x16& p1, const char* Kn, const char* Kr, const v8i32* qf, const float init, int r32, int hi) {
; #pragma unroll
;   for (int r = 0; r < 16; ++r) { p0[r] = init; p1[r] = init; }
; #pragma unroll
;   for (int s = 0; s < 2; ++s) { const int c0 = s * 4 + hi * 2;
;     const v8i32 a0 = cat8(*reinterpret_cast<const v4i32*>(Kn + KN8SW(r32, c0)), *reinterpret_cast<const v4i32*>(Kn + KN8SW(r32, c0 + 1)));
;     const v8i32 a1 = cat8(*reinterpret_cast<const v4i32*>(Kn + 4096 + KN8SW(r32, c0)), *reinterpret_cast<const v4i32*>(Kn + 4096 + KN8SW(r32, c0 + 1)));
;     p0 = __builtin_amdgcn_mfma_scale_f32_32x32x64_f8f6f4(a0, qf[s], p0, 0, 0, 0, 127, 0, 124);
;     p1 = __builtin_amdgcn_mfma_scale_f32_32x32x64_f8f6f4(a1, qf[s], p1, 0, 0, 0, 127, 0, 124); }
;   { const int c0 = hi * 2;
.Lmla_h3_cont:
	ds_read_b128 v[114:117], v215 offset:51200
	ds_read_b128 v[118:121], v216 offset:51200
	ds_read_b128 v[222:225], v215 offset:55296
	ds_read_b128 v[226:229], v216 offset:55296
	v_exp_f32_e32 v0, v82
	v_exp_f32_e32 v177, v83
	v_exp_f32_e32 v179, v84
	v_exp_f32_e32 v254, v85
	v_add_f32_e32 v219, v0, v177
	v_cvt_pk_fp8_f32 v246, v0, v177
	v_add_f32_e32 v219, v179, v219
	v_add_f32_e32 v219, v254, v219
	v_cvt_pk_fp8_f32 v246, v179, v254 op_sel:[0,0,1]
	s_waitcnt lgkmcnt(2)
	v_mfma_scale_f32_32x32x64_f8f6f4 v[114:129], v[114:121], v[146:153], v[230:245], v194, v193 op_sel_hi:[0,0,0]
	s_add_i32 m0, s98, 0x0
	s_nop 0
	global_load_lds_dwordx4 v176, s[18:19]
	s_add_i32 m0, s98, 0x4000
	s_nop 0
	global_load_lds_dwordx4 v178, s[16:17]
	s_add_i32 m0, s98, 0x8000
	s_nop 0
	global_load_lds_dwordx4 v[180:181], off
	v_exp_f32_e32 v0, v86
	v_exp_f32_e32 v177, v87
	v_exp_f32_e32 v179, v88
	v_exp_f32_e32 v254, v89
	v_add_f32_e32 v219, v0, v219
	v_add_f32_e32 v219, v177, v219
	v_cvt_pk_fp8_f32 v247, v0, v177
	v_add_f32_e32 v219, v179, v219
	v_add_f32_e32 v219, v254, v219
	v_cvt_pk_fp8_f32 v247, v179, v254 op_sel:[0,0,1]
	ds_read_b128 v[82:85], v213 offset:51200
	ds_read_b128 v[86:89], v214 offset:51200
	s_waitcnt lgkmcnt(2)
	v_mfma_scale_f32_32x32x64_f8f6f4 v[98:113], v[222:229], v[146:153], v[230:245], v194, v193 op_sel_hi:[0,0,0]
	ds_read_b128 v[222:225], v213 offset:55296
	ds_read_b128 v[226:229], v214 offset:55296
	v_exp_f32_e32 v0, v90
	v_exp_f32_e32 v177, v91
	v_exp_f32_e32 v179, v92
	v_exp_f32_e32 v254, v93
	v_add_f32_e32 v219, v0, v219
	v_add_f32_e32 v219, v177, v219
	v_cvt_pk_fp8_f32 v248, v0, v177
	v_add_f32_e32 v219, v179, v219
	v_add_f32_e32 v219, v254, v219
	v_cvt_pk_fp8_f32 v248, v179, v254 op_sel:[0,0,1]
	v_exp_f32_e32 v0, v94
	v_exp_f32_e32 v177, v95
	v_exp_f32_e32 v179, v96
	v_exp_f32_e32 v254, v97
	v_add_f32_e32 v219, v0, v219
	v_add_f32_e32 v219, v177, v219
	v_cvt_pk_fp8_f32 v249, v0, v177
	v_add_f32_e32 v219, v179, v219
	v_add_f32_e32 v219, v254, v219
	v_cvt_pk_fp8_f32 v249, v179, v254 op_sel:[0,0,1]
	ds_read_b128 v[90:93], v185 offset:59392
	ds_read_b128 v[94:97], v186 offset:59392
	s_waitcnt lgkmcnt(4)
	v_mfma_scale_f32_32x32x64_f8f6f4 v[114:129], v[82:89], v[138:145], v[114:129], v194, v193 op_sel_hi:[0,0,0]
	v_exp_f32_e32 v0, v66
	v_exp_f32_e32 v177, v67
	v_exp_f32_e32 v179, v68
	v_exp_f32_e32 v254, v69
	v_add_f32_e32 v219, v0, v219
	v_add_f32_e32 v219, v177, v219
	v_cvt_pk_fp8_f32 v250, v0, v177
	v_add_f32_e32 v219, v179, v219
	v_add_f32_e32 v219, v254, v219
	v_cvt_pk_fp8_f32 v250, v179, v254 op_sel:[0,0,1]
	s_waitcnt lgkmcnt(2)
	v_mfma_scale_f32_32x32x64_f8f6f4 v[98:113], v[222:229], v[138:145], v[98:113], v194, v193 op_sel_hi:[0,0,0]
	ds_read_b128 v[222:225], v185 offset:61440
	ds_read_b128 v[226:229], v186 offset:61440
	v_exp_f32_e32 v0, v70
	v_exp_f32_e32 v177, v71
	v_exp_f32_e32 v179, v72
	v_exp_f32_e32 v254, v73
	v_add_f32_e32 v219, v0, v219
	v_add_f32_e32 v219, v177, v219
	v_cvt_pk_fp8_f32 v251, v0, v177
	v_add_f32_e32 v219, v179, v219
	v_add_f32_e32 v219, v254, v219
	v_cvt_pk_fp8_f32 v251, v179, v254 op_sel:[0,0,1]
	v_exp_f32_e32 v0, v74
	v_exp_f32_e32 v177, v75
	v_exp_f32_e32 v179, v76
	v_exp_f32_e32 v254, v77
	v_add_f32_e32 v219, v0, v219
	v_add_f32_e32 v219, v177, v219
	v_cvt_pk_fp8_f32 v252, v0, v177
	v_add_f32_e32 v219, v179, v219
	v_add_f32_e32 v219, v254, v219
	v_cvt_pk_fp8_f32 v252, v179, v254 op_sel:[0,0,1]
	s_waitcnt lgkmcnt(2)
	v_mfma_scale_f32_32x32x64_f8f6f4 v[114:129], v[90:97], v[130:137], v[114:129], v194, v193 op_sel_hi:[0,0,0]
	v_exp_f32_e32 v0, v78
	v_exp_f32_e32 v177, v79
	v_exp_f32_e32 v179, v80
	v_exp_f32_e32 v254, v81
	v_add_f32_e32 v219, v0, v219
	v_add_f32_e32 v219, v177, v219
	v_cvt_pk_fp8_f32 v253, v0, v177
	v_add_f32_e32 v219, v179, v219
	v_add_f32_e32 v219, v254, v219
	v_cvt_pk_fp8_f32 v253, v179, v254 op_sel:[0,0,1]
	ds_read_b128 v[90:93], v185 offset:8192
	ds_read_b128 v[94:97], v186 offset:8192
	ds_read_b128 v[82:85], v185 offset:10240
	ds_read_b128 v[86:89], v186 offset:10240
	ds_read_b128 v[74:77], v185 offset:12288
	ds_read_b128 v[78:81], v186 offset:12288
	ds_read_b128 v[66:69], v185 offset:14336
	ds_read_b128 v[70:73], v186 offset:14336
	s_waitcnt lgkmcnt(8)
	v_mfma_scale_f32_32x32x64_f8f6f4 v[98:113], v[222:229], v[130:137], v[98:113], v194, v193 op_sel_hi:[0,0,0]
	v_mov_b32_e32 v0, v219
	s_nop 1
	v_permlane32_swap_b32_e32 v219, v0
	v_add_f32_e32 v219, v219, v0
	v_fma_f32 v209, v209, v218, v219
	v_add_u32_e32 v176, 0x2000, v176
	v_add_u32_e32 v178, 0x20000, v178
	s_mov_b64 s[20:21], 0x1000
	v_lshl_add_u64 v[180:181], v[180:181], 0, s[20:21]
	v_max_f32_e32 v177, v114, v115
	v_max3_f32 v177, v177, v116, v117
	v_max3_f32 v177, v177, v118, v119
	v_max3_f32 v177, v177, v120, v121
	v_max3_f32 v177, v177, v122, v123
	v_max3_f32 v177, v177, v124, v125
	v_max3_f32 v177, v177, v126, v127
	v_max3_f32 v177, v177, v128, v129
	s_waitcnt lgkmcnt(6)
	v_mfma_scale_f32_32x32x64_f8f6f4 v[50:65], v[246:253], v[90:97], v[50:65], v194, v194 op_sel_hi:[0,0,0]
	v_max_f32_e32 v0, v98, v99
	v_max3_f32 v0, v0, v100, v101
	v_max3_f32 v0, v0, v102, v103
	s_waitcnt lgkmcnt(4)
	v_mfma_scale_f32_32x32x64_f8f6f4 v[34:49], v[246:253], v[82:89], v[34:49], v194, v194 op_sel_hi:[0,0,0]
	v_max3_f32 v0, v0, v104, v105
	v_max3_f32 v0, v0, v106, v107
	v_max3_f32 v0, v0, v108, v109
	s_waitcnt lgkmcnt(2)
	v_mfma_scale_f32_32x32x64_f8f6f4 v[18:33], v[246:253], v[74:81], v[18:33], v194, v194 op_sel_hi:[0,0,0]
	v_max3_f32 v0, v0, v110, v111
	v_max3_f32 v0, v0, v112, v113
	v_max_f32_e32 v177, v177, v0
	v_mov_b32_e32 v0, v177
	v_mov_b32_e32 v221, 1.0
	s_waitcnt lgkmcnt(0)
	v_mfma_scale_f32_32x32x64_f8f6f4 v[2:17], v[246:253], v[66:73], v[2:17], v194, v194 op_sel_hi:[0,0,0]
	s_waitcnt vmcnt(0)
	s_waitcnt lgkmcnt(0)
	s_barrier
	v_permlane32_swap_b32_e32 v177, v0
	v_max_f32_e32 v177, v177, v0
	v_cmp_ge_f32_e32 vcc, s90, v177
	s_cmp_eq_u64 vcc, exec
	s_cbranch_scc0 .Lmla_h4_newmax
; __device__ __forceinline__ void finishSM9(f32x16& p0, f32x16& p1, float alpha, float& l_reg, v8i32& p8) {
; #pragma unroll
;   for (int r = 0; r < 16; ++r) { p0[r] = __builtin_amdgcn_exp2f(p0[r]); p1[r] = __builtin_amdgcn_exp2f(p1[r]); }
;   float ps = 0;
; #pragma unroll
;   for (int r = 0; r < 16; ++r) ps += p0[r];
; #pragma unroll
;   for (int r = 0; r < 16; ++r) ps += p1[r];
;   { auto rr = __builtin_amdgcn_permlane32_swap(__float_as_uint(ps), __float_as_uint(ps), false, false);
;     ps = __uint_as_float(rr[0]) + __uint_as_float(rr[1]); }
;   l_reg = l_reg * alpha + ps;
; #pragma unroll
;   for (int g = 0; g < 4; ++g) {
;     int w = __builtin_amdgcn_cvt_pk_fp8_f32(p0[4 * g], p0[4 * g + 1], 0, false); p8[g] = __builtin_amdgcn_cvt_pk_fp8_f32(p0[4 * g + 2], p0[4 * g + 3], w, true);
;     int u = __builtin_amdgcn_cvt_pk_fp8_f32(p1[4 * g], p1[4 * g + 1], 0, false); p8[4 + g] = __builtin_amdgcn_cvt_pk_fp8_f32(p1[4 * g + 2], p1[4 * g + 3], u, true); }
; }
; __device__ __forceinline__ void pv8(f32x16* o, const char* Vt, const v8i32 p8, int r32, int hi) {
;   const int sw = (r32 >> 2) & 3, a0 = r32 * 64 + (((hi * 2) ^ sw) << 4), a1 = r32 * 64 + (((hi * 2 + 1) ^ sw) << 4);
; #pragma unroll
;   for (int d0 = 0; d0 < 4; ++d0) {
;     const v8i32 vf = cat8(*reinterpret_cast<const v4i32*>(Vt + d0 * 2048 + a0), *reinterpret_cast<const v4i32*>(Vt + d0 * 2048 + a1));
;     o[d0] = __builtin_amdgcn_mfma_scale_f32_32x32x64_f8f6f4(p8, vf, o[d0], 0, 0, 0, 127, 0, 127); }
; }
; __device__ __forceinline__ void qkt9(f32x16& p0, f32x16& p1, const char* Kn, const char* Kr, const v8i32* qf, const float init, int r32, int hi) {
; #pragma unroll
;   for (int r = 0; r < 16; ++r) { p0[r] = init; p1[r] = init; }
; #pragma unroll
;   for (int s = 0; s < 2; ++s) { const int c0 = s * 4 + hi * 2;
;     const v8i32 a0 = cat8(*reinterpret_cast<const v4i32*>(Kn + KN8SW(r32, c0)), *reinterpret_cast<const v4i32*>(Kn + KN8SW(r32, c0 + 1)));
;     const v8i32 a1 = cat8(*reinterpret_cast<const v4i32*>(Kn + 4096 + KN8SW(r32, c0)), *reinterpret_cast<const v4i32*>(Kn + 4096 + KN8SW(r32, c0 + 1)));
;     p0 = __builtin_amdgcn_mfma_scale_f32_32x32x64_f8f6f4(a0, qf[s], p0, 0, 0, 0, 127, 0, 124);
;     p1 = __builtin_amdgcn_mfma_scale_f32_32x32x64_f8f6f4(a1, qf[s], p1, 0, 0, 0, 127, 0, 124); }
;   { const int c0 = hi * 2;
.Lmla_h4_cont:
	ds_read_b128 v[82:85], v215 offset:16384
	ds_read_b128 v[86:89], v216 offset:16384
	ds_read_b128 v[222:225], v215 offset:20480
	ds_read_b128 v[226:229], v216 offset:20480
	v_exp_f32_e32 v0, v114
	v_exp_f32_e32 v177, v115
	v_exp_f32_e32 v179, v116
	v_exp_f32_e32 v254, v117
	v_add_f32_e32 v219, v0, v177
	v_cvt_pk_fp8_f32 v246, v0, v177
	v_add_f32_e32 v219, v179, v219
	v_add_f32_e32 v219, v254, v219
	v_cvt_pk_fp8_f32 v246, v179, v254 op_sel:[0,0,1]
	s_waitcnt lgkmcnt(2)
	v_mfma_scale_f32_32x32x64_f8f6f4 v[82:97], v[82:89], v[146:153], v[230:245], v194, v193 op_sel_hi:[0,0,0]
	s_add_i32 m0, s98, 0x2000
	s_nop 0
	global_load_lds_dwordx4 v176, s[18:19]
	s_add_i32 m0, s98, 0x6000
	s_nop 0
	global_load_lds_dwordx4 v178, s[16:17]
	s_add_i32 m0, s98, 0x9000
	s_nop 0
	global_load_lds_dwordx4 v[180:181], off
	v_exp_f32_e32 v0, v118
	v_exp_f32_e32 v177, v119
	v_exp_f32_e32 v179, v120
	v_exp_f32_e32 v254, v121
	v_add_f32_e32 v219, v0, v219
	v_add_f32_e32 v219, v177, v219
	v_cvt_pk_fp8_f32 v247, v0, v177
	v_add_f32_e32 v219, v179, v219
	v_add_f32_e32 v219, v254, v219
	v_cvt_pk_fp8_f32 v247, v179, v254 op_sel:[0,0,1]
	ds_read_b128 v[114:117], v213 offset:16384
	ds_read_b128 v[118:121], v214 offset:16384
	s_waitcnt lgkmcnt(2)
	v_mfma_scale_f32_32x32x64_f8f6f4 v[66:81], v[222:229], v[146:153], v[230:245], v194, v193 op_sel_hi:[0,0,0]
	ds_read_b128 v[222:225], v213 offset:20480
	ds_read_b128 v[226:229], v214 offset:20480
	v_exp_f32_e32 v0, v122
	v_exp_f32_e32 v177, v123
	v_exp_f32_e32 v179, v124
	v_exp_f32_e32 v254, v125
	v_add_f32_e32 v219, v0, v219
	v_add_f32_e32 v219, v177, v219
	v_cvt_pk_fp8_f32 v248, v0, v177
	v_add_f32_e32 v219, v179, v219
	v_add_f32_e32 v219, v254, v219
	v_cvt_pk_fp8_f32 v248, v179, v254 op_sel:[0,0,1]
	v_exp_f32_e32 v0, v126
	v_exp_f32_e32 v177, v127
	v_exp_f32_e32 v179, v128
	v_exp_f32_e32 v254, v129
	v_add_f32_e32 v219, v0, v219
	v_add_f32_e32 v219, v177, v219
	v_cvt_pk_fp8_f32 v249, v0, v177
	v_add_f32_e32 v219, v179, v219
	v_add_f32_e32 v219, v254, v219
	v_cvt_pk_fp8_f32 v249, v179, v254 op_sel:[0,0,1]
	ds_read_b128 v[122:125], v185 offset:32768
	ds_read_b128 v[126:129], v186 offset:32768
	s_waitcnt lgkmcnt(4)
	v_mfma_scale_f32_32x32x64_f8f6f4 v[82:97], v[114:121], v[138:145], v[82:97], v194, v193 op_sel_hi:[0,0,0]
	v_exp_f32_e32 v0, v98
	v_exp_f32_e32 v177, v99
	v_exp_f32_e32 v179, v100
	v_exp_f32_e32 v254, v101
	v_add_f32_e32 v219, v0, v219
	v_add_f32_e32 v219, v177, v219
	v_cvt_pk_fp8_f32 v250, v0, v177
	v_add_f32_e32 v219, v179, v219
	v_add_f32_e32 v219, v254, v219
	v_cvt_pk_fp8_f32 v250, v179, v254 op_sel:[0,0,1]
	s_waitcnt lgkmcnt(2)
	v_mfma_scale_f32_32x32x64_f8f6f4 v[66:81], v[222:229], v[138:145], v[66:81], v194, v193 op_sel_hi:[0,0,0]
	ds_read_b128 v[222:225], v185 offset:34816
	ds_read_b128 v[226:229], v186 offset:34816
	v_exp_f32_e32 v0, v102
	v_exp_f32_e32 v177, v103
	v_exp_f32_e32 v179, v104
	v_exp_f32_e32 v254, v105
	v_add_f32_e32 v219, v0, v219
	v_add_f32_e32 v219, v177, v219
	v_cvt_pk_fp8_f32 v251, v0, v177
	v_add_f32_e32 v219, v179, v219
	v_add_f32_e32 v219, v254, v219
	v_cvt_pk_fp8_f32 v251, v179, v254 op_sel:[0,0,1]
	v_exp_f32_e32 v0, v106
	v_exp_f32_e32 v177, v107
	v_exp_f32_e32 v179, v108
	v_exp_f32_e32 v254, v109
	v_add_f32_e32 v219, v0, v219
	v_add_f32_e32 v219, v177, v219
	v_cvt_pk_fp8_f32 v252, v0, v177
	v_add_f32_e32 v219, v179, v219
	v_add_f32_e32 v219, v254, v219
	v_cvt_pk_fp8_f32 v252, v179, v254 op_sel:[0,0,1]
	s_waitcnt lgkmcnt(2)
	v_mfma_scale_f32_32x32x64_f8f6f4 v[82:97], v[122:129], v[130:137], v[82:97], v194, v193 op_sel_hi:[0,0,0]
	v_exp_f32_e32 v0, v110
	v_exp_f32_e32 v177, v111
	v_exp_f32_e32 v179, v112
	v_exp_f32_e32 v254, v113
	v_add_f32_e32 v219, v0, v219
	v_add_f32_e32 v219, v177, v219
	v_cvt_pk_fp8_f32 v253, v0, v177
	v_add_f32_e32 v219, v179, v219
	v_add_f32_e32 v219, v254, v219
	v_cvt_pk_fp8_f32 v253, v179, v254 op_sel:[0,0,1]
	ds_read_b128 v[122:125], v185 offset:43008
	ds_read_b128 v[126:129], v186 offset:43008
	ds_read_b128 v[114:117], v185 offset:45056
	ds_read_b128 v[118:121], v186 offset:45056
	ds_read_b128 v[106:109], v185 offset:47104
	ds_read_b128 v[110:113], v186 offset:47104
	ds_read_b128 v[98:101], v185 offset:49152
	ds_read_b128 v[102:105], v186 offset:49152
	s_waitcnt lgkmcnt(8)
	v_mfma_scale_f32_32x32x64_f8f6f4 v[66:81], v[222:229], v[130:137], v[66:81], v194, v193 op_sel_hi:[0,0,0]
	v_mov_b32_e32 v0, v219
	s_nop 1
	v_permlane32_swap_b32_e32 v219, v0
	v_add_f32_e32 v219, v219, v0
	v_fma_f32 v209, v209, v221, v219
	v_add_u32_e32 v176, 0x2000, v176
	v_add_u32_e32 v178, 0x20000, v178
	s_mov_b64 s[20:21], 0x1000
	v_lshl_add_u64 v[180:181], v[180:181], 0, s[20:21]
	v_max_f32_e32 v177, v82, v83
	v_max3_f32 v177, v177, v84, v85
	v_max3_f32 v177, v177, v86, v87
	v_max3_f32 v177, v177, v88, v89
	v_max3_f32 v177, v177, v90, v91
	v_max3_f32 v177, v177, v92, v93
	v_max3_f32 v177, v177, v94, v95
	v_max3_f32 v177, v177, v96, v97
	s_waitcnt lgkmcnt(6)
	v_mfma_scale_f32_32x32x64_f8f6f4 v[50:65], v[246:253], v[122:129], v[50:65], v194, v194 op_sel_hi:[0,0,0]
	v_max_f32_e32 v0, v66, v67
	v_max3_f32 v0, v0, v68, v69
	v_max3_f32 v0, v0, v70, v71
	s_waitcnt lgkmcnt(4)
	v_mfma_scale_f32_32x32x64_f8f6f4 v[34:49], v[246:253], v[114:121], v[34:49], v194, v194 op_sel_hi:[0,0,0]
	v_max3_f32 v0, v0, v72, v73
	v_max3_f32 v0, v0, v74, v75
	v_max3_f32 v0, v0, v76, v77
	s_waitcnt lgkmcnt(2)
	v_mfma_scale_f32_32x32x64_f8f6f4 v[18:33], v[246:253], v[106:113], v[18:33], v194, v194 op_sel_hi:[0,0,0]
	v_max3_f32 v0, v0, v78, v79
	v_max3_f32 v0, v0, v80, v81
	v_max_f32_e32 v177, v177, v0
	v_mov_b32_e32 v0, v177
	v_mov_b32_e32 v218, 1.0
	s_waitcnt lgkmcnt(0)
	v_mfma_scale_f32_32x32x64_f8f6f4 v[2:17], v[246:253], v[98:105], v[2:17], v194, v194 op_sel_hi:[0,0,0]
	s_waitcnt vmcnt(0)
	s_waitcnt lgkmcnt(0)
	s_barrier
	v_permlane32_swap_b32_e32 v177, v0
	v_max_f32_e32 v177, v177, v0
	v_cmp_ge_f32_e32 vcc, s90, v177
	s_cmp_eq_u64 vcc, exec
	s_cbranch_scc0 .Lmla_h5_newmax
; __device__ __forceinline__ void finishSM9(f32x16& p0, f32x16& p1, float alpha, float& l_reg, v8i32& p8) {
; #pragma unroll
;   for (int r = 0; r < 16; ++r) { p0[r] = __builtin_amdgcn_exp2f(p0[r]); p1[r] = __builtin_amdgcn_exp2f(p1[r]); }
;   float ps = 0;
; #pragma unroll
;   for (int r = 0; r < 16; ++r) ps += p0[r];
; #pragma unroll
;   for (int r = 0; r < 16; ++r) ps += p1[r];
;   { auto rr = __builtin_amdgcn_permlane32_swap(__float_as_uint(ps), __float_as_uint(ps), false, false);
;     ps = __uint_as_float(rr[0]) + __uint_as_float(rr[1]); }
;   l_reg = l_reg * alpha + ps;
; #pragma unroll
;   for (int g = 0; g < 4; ++g) {
;     int w = __builtin_amdgcn_cvt_pk_fp8_f32(p0[4 * g], p0[4 * g + 1], 0, false); p8[g] = __builtin_amdgcn_cvt_pk_fp8_f32(p0[4 * g + 2], p0[4 * g + 3], w, true);
;     int u = __builtin_amdgcn_cvt_pk_fp8_f32(p1[4 * g], p1[4 * g + 1], 0, false); p8[4 + g] = __builtin_amdgcn_cvt_pk_fp8_f32(p1[4 * g + 2], p1[4 * g + 3], u, true); }
; }
; __device__ __forceinline__ void pv8(f32x16* o, const char* Vt, const v8i32 p8, int r32, int hi) {
;   const int sw = (r32 >> 2) & 3, a0 = r32 * 64 + (((hi * 2) ^ sw) << 4), a1 = r32 * 64 + (((hi * 2 + 1) ^ sw) << 4);
; #pragma unroll
;   for (int d0 = 0; d0 < 4; ++d0) {
;     const v8i32 vf = cat8(*reinterpret_cast<const v4i32*>(Vt + d0 * 2048 + a0), *reinterpret_cast<const v4i32*>(Vt + d0 * 2048 + a1));
;     o[d0] = __builtin_amdgcn_mfma_scale_f32_32x32x64_f8f6f4(p8, vf, o[d0], 0, 0, 0, 127, 0, 127); }
; }
; __device__ __forceinline__ void qkt9(f32x16& p0, f32x16& p1, const char* Kn, const char* Kr, const v8i32* qf, const float init, int r32, int hi) {
; #pragma unroll
;   for (int r = 0; r < 16; ++r) { p0[r] = init; p1[r] = init; }
; #pragma unroll
;   for (int s = 0; s < 2; ++s) { const int c0 = s * 4 + hi * 2;
;     const v8i32 a0 = cat8(*reinterpret_cast<const v4i32*>(Kn + KN8SW(r32, c0)), *reinterpret_cast<const v4i32*>(Kn + KN8SW(r32, c0 + 1)));
;     const v8i32 a1 = cat8(*reinterpret_cast<const v4i32*>(Kn + 4096 + KN8SW(r32, c0)), *reinterpret_cast<const v4i32*>(Kn + 4096 + KN8SW(r32, c0 + 1)));
;     p0 = __builtin_amdgcn_mfma_scale_f32_32x32x64_f8f6f4(a0, qf[s], p0, 0, 0, 0, 127, 0, 124);
;     p1 = __builtin_amdgcn_mfma_scale_f32_32x32x64_f8f6f4(a1, qf[s], p1, 0, 0, 0, 127, 0, 124); }
;   { const int c0 = hi * 2;
.Lmla_h5_cont:
	s_add_i32 s30, s30, 1
	s_cmpk_lt_u32 s30, 42
	s_cbranch_scc1 .LBB0_1321
	ds_read_b128 v[114:117], v215 offset:24576
	ds_read_b128 v[118:121], v216 offset:24576
	ds_read_b128 v[222:225], v215 offset:28672
	ds_read_b128 v[226:229], v216 offset:28672
	v_exp_f32_e32 v0, v82
	v_exp_f32_e32 v177, v83
	v_exp_f32_e32 v179, v84
	v_exp_f32_e32 v254, v85
	v_add_f32_e32 v219, v0, v177
	v_cvt_pk_fp8_f32 v246, v0, v177
	v_add_f32_e32 v219, v179, v219
	v_add_f32_e32 v219, v254, v219
	v_cvt_pk_fp8_f32 v246, v179, v254 op_sel:[0,0,1]
	s_waitcnt lgkmcnt(2)
	v_mfma_scale_f32_32x32x64_f8f6f4 v[114:129], v[114:121], v[146:153], v[230:245], v194, v193 op_sel_hi:[0,0,0]
	s_add_i32 m0, s98, 0xa800
	s_nop 0
	global_load_lds_dwordx4 v176, s[18:19]
	s_add_i32 m0, s98, 0xc800
	s_nop 0
	global_load_lds_dwordx4 v178, s[16:17]
	s_add_i32 m0, s98, 0xe800
	s_nop 0
	global_load_lds_dwordx4 v[180:181], off
	v_exp_f32_e32 v0, v86
	v_exp_f32_e32 v177, v87
	v_exp_f32_e32 v179, v88
	v_exp_f32_e32 v254, v89
	v_add_f32_e32 v219, v0, v219
	v_add_f32_e32 v219, v177, v219
	v_cvt_pk_fp8_f32 v247, v0, v177
	v_add_f32_e32 v219, v179, v219
	v_add_f32_e32 v219, v254, v219
	v_cvt_pk_fp8_f32 v247, v179, v254 op_sel:[0,0,1]
	ds_read_b128 v[82:85], v213 offset:24576
	ds_read_b128 v[86:89], v214 offset:24576
	s_waitcnt lgkmcnt(2)
	v_mfma_scale_f32_32x32x64_f8f6f4 v[98:113], v[222:229], v[146:153], v[230:245], v194, v193 op_sel_hi:[0,0,0]
	ds_read_b128 v[222:225], v213 offset:28672
	ds_read_b128 v[226:229], v214 offset:28672
	v_exp_f32_e32 v0, v90
	v_exp_f32_e32 v177, v91
	v_exp_f32_e32 v179, v92
	v_exp_f32_e32 v254, v93
	v_add_f32_e32 v219, v0, v219
	v_add_f32_e32 v219, v177, v219
	v_cvt_pk_fp8_f32 v248, v0, v177
	v_add_f32_e32 v219, v179, v219
	v_add_f32_e32 v219, v254, v219
	v_cvt_pk_fp8_f32 v248, v179, v254 op_sel:[0,0,1]
	v_exp_f32_e32 v0, v94
	v_exp_f32_e32 v177, v95
	v_exp_f32_e32 v179, v96
	v_exp_f32_e32 v254, v97
	v_add_f32_e32 v219, v0, v219
	v_add_f32_e32 v219, v177, v219
	v_cvt_pk_fp8_f32 v249, v0, v177
	v_add_f32_e32 v219, v179, v219
	v_add_f32_e32 v219, v254, v219
	v_cvt_pk_fp8_f32 v249, v179, v254 op_sel:[0,0,1]
	ds_read_b128 v[90:93], v185 offset:36864
	ds_read_b128 v[94:97], v186 offset:36864
	s_waitcnt lgkmcnt(4)
	v_mfma_scale_f32_32x32x64_f8f6f4 v[114:129], v[82:89], v[138:145], v[114:129], v194, v193 op_sel_hi:[0,0,0]
	v_exp_f32_e32 v0, v66
	v_exp_f32_e32 v177, v67
	v_exp_f32_e32 v179, v68
	v_exp_f32_e32 v254, v69
	v_add_f32_e32 v219, v0, v219
	v_add_f32_e32 v219, v177, v219
	v_cvt_pk_fp8_f32 v250, v0, v177
	v_add_f32_e32 v219, v179, v219
	v_add_f32_e32 v219, v254, v219
	v_cvt_pk_fp8_f32 v250, v179, v254 op_sel:[0,0,1]
	s_waitcnt lgkmcnt(2)
	v_mfma_scale_f32_32x32x64_f8f6f4 v[98:113], v[222:229], v[138:145], v[98:113], v194, v193 op_sel_hi:[0,0,0]
	ds_read_b128 v[222:225], v185 offset:38912
	ds_read_b128 v[226:229], v186 offset:38912
	v_exp_f32_e32 v0, v70
	v_exp_f32_e32 v177, v71
	v_exp_f32_e32 v179, v72
	v_exp_f32_e32 v254, v73
	v_add_f32_e32 v219, v0, v219
	v_add_f32_e32 v219, v177, v219
	v_cvt_pk_fp8_f32 v251, v0, v177
	v_add_f32_e32 v219, v179, v219
	v_add_f32_e32 v219, v254, v219
	v_cvt_pk_fp8_f32 v251, v179, v254 op_sel:[0,0,1]
	v_exp_f32_e32 v0, v74
	v_exp_f32_e32 v177, v75
	v_exp_f32_e32 v179, v76
	v_exp_f32_e32 v254, v77
	v_add_f32_e32 v219, v0, v219
	v_add_f32_e32 v219, v177, v219
	v_cvt_pk_fp8_f32 v252, v0, v177
	v_add_f32_e32 v219, v179, v219
	v_add_f32_e32 v219, v254, v219
	v_cvt_pk_fp8_f32 v252, v179, v254 op_sel:[0,0,1]
	s_waitcnt lgkmcnt(2)
	v_mfma_scale_f32_32x32x64_f8f6f4 v[114:129], v[90:97], v[130:137], v[114:129], v194, v193 op_sel_hi:[0,0,0]
	v_exp_f32_e32 v0, v78
	v_exp_f32_e32 v177, v79
	v_exp_f32_e32 v179, v80
	v_exp_f32_e32 v254, v81
	v_add_f32_e32 v219, v0, v219
	v_add_f32_e32 v219, v177, v219
	v_cvt_pk_fp8_f32 v253, v0, v177
	v_add_f32_e32 v219, v179, v219
	v_add_f32_e32 v219, v254, v219
	v_cvt_pk_fp8_f32 v253, v179, v254 op_sel:[0,0,1]
	ds_read_b128 v[90:93], v185 offset:0
	ds_read_b128 v[94:97], v186 offset:0
	ds_read_b128 v[82:85], v185 offset:2048
	ds_read_b128 v[86:89], v186 offset:2048
	ds_read_b128 v[74:77], v185 offset:4096
	ds_read_b128 v[78:81], v186 offset:4096
	ds_read_b128 v[66:69], v185 offset:6144
	ds_read_b128 v[70:73], v186 offset:6144
	s_waitcnt lgkmcnt(8)
	v_mfma_scale_f32_32x32x64_f8f6f4 v[98:113], v[222:229], v[130:137], v[98:113], v194, v193 op_sel_hi:[0,0,0]
	v_mov_b32_e32 v0, v219
	s_nop 1
	v_permlane32_swap_b32_e32 v219, v0
	v_add_f32_e32 v219, v219, v0
	v_fma_f32 v209, v209, v218, v219
	v_add_u32_e32 v176, 0x2000, v176
	v_add_u32_e32 v178, 0x20000, v178
	s_mov_b64 s[20:21], 0x1000
	v_lshl_add_u64 v[180:181], v[180:181], 0, s[20:21]
	v_max_f32_e32 v177, v114, v115
	v_max3_f32 v177, v177, v116, v117
	v_max3_f32 v177, v177, v118, v119
	v_max3_f32 v177, v177, v120, v121
	v_max3_f32 v177, v177, v122, v123
	v_max3_f32 v177, v177, v124, v125
	v_max3_f32 v177, v177, v126, v127
	v_max3_f32 v177, v177, v128, v129
	s_waitcnt lgkmcnt(6)
	v_mfma_scale_f32_32x32x64_f8f6f4 v[50:65], v[246:253], v[90:97], v[50:65], v194, v194 op_sel_hi:[0,0,0]
	v_max_f32_e32 v0, v98, v99
	v_max3_f32 v0, v0, v100, v101
	v_max3_f32 v0, v0, v102, v103
	s_waitcnt lgkmcnt(4)
	v_mfma_scale_f32_32x32x64_f8f6f4 v[34:49], v[246:253], v[82:89], v[34:49], v194, v194 op_sel_hi:[0,0,0]
	v_max3_f32 v0, v0, v104, v105
	v_max3_f32 v0, v0, v106, v107
	v_max3_f32 v0, v0, v108, v109
	s_waitcnt lgkmcnt(2)
	v_mfma_scale_f32_32x32x64_f8f6f4 v[18:33], v[246:253], v[74:81], v[18:33], v194, v194 op_sel_hi:[0,0,0]
	v_max3_f32 v0, v0, v110, v111
	v_max3_f32 v0, v0, v112, v113
	v_max_f32_e32 v177, v177, v0
	v_mov_b32_e32 v0, v177
	v_mov_b32_e32 v221, 1.0
	s_waitcnt lgkmcnt(0)
	v_mfma_scale_f32_32x32x64_f8f6f4 v[2:17], v[246:253], v[66:73], v[2:17], v194, v194 op_sel_hi:[0,0,0]
	s_waitcnt vmcnt(0)
	s_waitcnt lgkmcnt(0)
	s_barrier
	v_permlane32_swap_b32_e32 v177, v0
	v_max_f32_e32 v177, v177, v0
	v_cmp_ge_f32_e32 vcc, s90, v177
	s_cmp_eq_u64 vcc, exec
	s_cbranch_scc0 .Lmla_p0_newmax
